# rope loop unrolled x2 with two prefetch sets (distance 2) on top of v16 stack
# speedup vs baseline: 1.0222x; 1.0056x over previous
.LBB0_947:
	s_or_b64 exec, exec, s[0:1]
	v_mov_b32_e32 v32, v206
	s_mov_b32 s2, s49
	s_waitcnt lgkmcnt(0)
	s_barrier
	s_add_u32 s4, s86, s2
	v_readfirstlane_b32 s0, v32
	s_addc_u32 s5, s87, 0
	s_ashr_i32 s14, s0, 6
	s_add_i32 s20, s14, s97
	v_and_b32_e32 v33, 7, v32
	v_bfe_u32 v30, v32, 3, 3
	s_cmpk_gt_i32 s20, 0x7fff
	v_lshlrev_b32_e32 v31, 1, v33
	s_cbranch_scc1 .LBB0_950
	v_cvt_f32_ubyte0_e32 v0, v31
	v_mul_f32_e32 v1, 0xbf549a78, v0
	s_mov_b32 s0, 0xc2fc0000
	v_cmp_gt_f32_e32 vcc, s0, v1
	v_mov_b32_e32 v3, 0x42800000
	s_mov_b32 s3, s49
	v_cndmask_b32_e32 v1, 0, v3, vcc
	v_fmac_f32_e32 v1, 0xbf549a78, v0
	v_exp_f32_e32 v0, v1
	v_or_b32_e32 v1, 1, v31
	v_cvt_f32_ubyte0_e32 v1, v1
	v_mul_f32_e32 v2, 0xbf549a78, v1
	v_cmp_gt_f32_e64 s[0:1], s0, v2
	s_mov_b32 s7, s49
	v_readlane_b32 s36, v252, 21
	v_cndmask_b32_e64 v2, 0, v3, s[0:1]
	v_fmac_f32_e32 v2, 0xbf549a78, v1
	v_exp_f32_e32 v1, v2
	v_not_b32_e32 v3, 63
	v_cndmask_b32_e32 v2, 0, v3, vcc
	v_ldexp_f32 v34, v0, v2
	v_cndmask_b32_e64 v0, 0, v3, s[0:1]
	v_lshlrev_b32_e32 v148, 3, v33
	s_add_u32 s0, s4, 0xf600000
	v_lshrrev_b32_e32 v2, 2, v33
	v_lshlrev_b32_e32 v8, 5, v33
	v_mov_b32_e32 v9, v149
	v_readlane_b32 s48, v252, 33
	v_readlane_b32 s49, v252, 34
	v_ldexp_f32 v35, v1, v0
	v_and_b32_e32 v1, 64, v210
	s_addc_u32 s1, s5, 0
	v_or_b32_e32 v39, 8, v2
	v_or_b32_e32 v40, 10, v2
	v_lshl_add_u64 v[2:3], s[48:49], 0, v[8:9]
	v_lshl_add_u64 v[4:5], s[48:49], 0, v[148:149]
	s_mov_b32 s49, s7
	s_ashr_i32 s7, s14, 31
	v_xor_b32_e32 v0, 1, v210
	v_add_u32_e32 v1, 64, v1
	s_add_u32 s6, s97, s14
	v_readlane_b32 s8, v253, 44
	v_cmp_lt_i32_e32 vcc, v0, v1
	s_addc_u32 s7, s8, s7
	v_readlane_b32 s50, v252, 35
	v_cndmask_b32_e32 v0, v210, v0, vcc
	v_readlane_b32 s51, v252, 36
	s_lshl_b64 s[8:9], s[6:7], 11
	v_and_b32_e32 v10, 56, v32
	v_lshlrev_b32_e32 v36, 2, v0
	v_xor_b32_e32 v0, 2, v210
	v_lshl_add_u64 v[6:7], s[50:51], 0, v[148:149]
	v_lshl_or_b32 v14, v10, 5, s8
	v_lshlrev_b32_e32 v148, 2, v33
	v_cmp_lt_i32_e32 vcc, v0, v1
	v_or_b32_e32 v12, v14, v148
	v_mov_b32_e32 v13, s9
	v_lshlrev_b32_e32 v17, 4, v33
	v_readlane_b32 s8, v253, 47
	v_cndmask_b32_e32 v0, v210, v0, vcc
	v_lshl_add_u64 v[10:11], s[86:87], 0, v[12:13]
	v_or_b32_e32 v12, v14, v17
	v_readlane_b32 s9, v253, 48
	s_lshl_b64 s[6:7], s[6:7], 10
	v_lshlrev_b32_e32 v37, 2, v0
	v_xor_b32_e32 v0, 4, v210
	v_lshlrev_b32_e32 v16, 7, v30
	v_lshl_add_u64 v[12:13], s[8:9], 0, v[12:13]
	s_add_u32 s8, s86, s6
	v_cmp_lt_i32_e32 vcc, v0, v1
	s_addc_u32 s9, s87, s7
	v_or3_b32 v16, s6, v16, v17
	v_mov_b32_e32 v17, s7
	v_readlane_b32 s6, v253, 51
	v_cndmask_b32_e32 v0, v210, v0, vcc
	v_readlane_b32 s7, v253, 52
	v_lshlrev_b32_e32 v38, 2, v0
	v_lshlrev_b32_e32 v0, 2, v32
	s_mov_b32 s18, 0x6dc9c883
	v_readlane_b32 s16, v253, 49
	v_readlane_b32 s12, v253, 45
	v_lshl_add_u64 v[16:17], s[6:7], 0, v[16:17]
	s_lshl_b32 s6, s14, 1
	v_readlane_b32 s7, v253, 23
	v_and_b32_e32 v0, 12, v0
	v_mov_b32_e32 v1, v149
	s_mov_b32 s19, 0x3fc45f30
	v_readlane_b32 s17, v253, 50
	v_readlane_b32 s13, v253, 46
	v_readlane_b32 s36, v254, 30
	v_readlane_b32 s31, v254, 29
	v_lshl_add_u64 v[8:9], s[50:51], 0, v[8:9]
	v_lshl_add_u64 v[14:15], s[8:9], 0, v[148:149]
	s_add_i32 s6, s7, s6
	s_mov_b32 s7, s20
	v_readlane_b32 s37, v252, 22
	v_readlane_b32 s38, v252, 23
	v_readlane_b32 s39, v252, 24
	v_readlane_b32 s40, v252, 25
	v_readlane_b32 s41, v252, 26
	v_readlane_b32 s42, v252, 27
	v_readlane_b32 s43, v252, 28
	v_readlane_b32 s44, v252, 29
	v_readlane_b32 s45, v252, 30
	v_readlane_b32 s46, v252, 31
	v_readlane_b32 s47, v252, 32
	s_mov_b32 s22, 0x1b600000
	s_mov_b32 s23, 0
	s_mov_b32 s24, 0x12600000
	s_mov_b32 s25, 0
	global_load_dwordx4 v[80:83], v[2:3], off
	global_load_dwordx4 v[84:87], v[2:3], off offset:16
	global_load_dwordx2 v[88:89], v[4:5], off offset:256
	global_load_dwordx2 v[90:91], v[4:5], off offset:320
	global_load_dwordx2 v[92:93], v[6:7], off offset:256
	global_load_dwordx2 v[94:95], v[6:7], off offset:320
	global_load_dwordx4 v[96:99], v[8:9], off
	global_load_dwordx4 v[100:103], v[8:9], off offset:16
	v_lshl_add_u64 v[122:123], v[12:13], 0, s[2:3]
	global_load_dwordx4 v[104:107], v[122:123], off
	v_lshl_add_u64 v[124:125], v[10:11], 0, s[2:3]
	v_lshl_add_u64 v[124:125], v[124:125], 0, s[22:23]
	global_load_dword v108, v[124:125], off offset:128
	global_load_dword v109, v[124:125], off offset:160
	v_lshl_add_u64 v[122:123], v[14:15], 0, s[2:3]
	v_lshl_add_u64 v[122:123], v[122:123], 0, s[24:25]
	global_load_dword v110, v[122:123], off offset:800
	global_load_dword v111, v[122:123], off offset:768
	v_lshl_add_u64 v[124:125], v[16:17], 0, s[2:3]
	global_load_dwordx4 v[112:115], v[124:125], off
	s_add_i32 s26, s7, s84
	s_cmpk_gt_i32 s26, 0x7fff
	s_cbranch_scc1 .Lrope_pro_done
	v_lshl_add_u64 v[122:123], v[12:13], 0, s[2:3]
	v_lshl_add_u64 v[122:123], v[122:123], 0, s[12:13]
	global_load_dwordx4 v[116:119], v[122:123], off
	v_lshl_add_u64 v[124:125], v[10:11], 0, s[2:3]
	v_lshl_add_u64 v[124:125], v[124:125], 0, s[12:13]
	v_lshl_add_u64 v[124:125], v[124:125], 0, s[22:23]
	global_load_dword v120, v[124:125], off offset:128
	global_load_dword v121, v[124:125], off offset:160
	v_lshl_add_u64 v[122:123], v[14:15], 0, s[2:3]
	v_lshl_add_u64 v[122:123], v[122:123], 0, s[16:17]
	v_lshl_add_u64 v[122:123], v[122:123], 0, s[24:25]
	global_load_dword v126, v[122:123], off offset:800
	global_load_dword v127, v[122:123], off offset:768
	v_lshl_add_u64 v[124:125], v[16:17], 0, s[2:3]
	v_lshl_add_u64 v[124:125], v[124:125], 0, s[16:17]
	global_load_dwordx4 v[128:131], v[124:125], off

.LBB0_949:
	s_and_b32 s8, s7, 0xfff
	s_add_i32 s8, s8, 16
	v_cvt_f32_u32_e32 v22, s8
	s_and_b32 s8, s7, 51
	s_and_b32 s9, s6, 8
	s_or_b32 s8, s9, s8
	v_mul_f32_e32 v18, v34, v22
	v_cvt_f64_f32_e32 v[18:19], v18
	v_mul_f64 v[20:21], v[18:19], s[18:19]
	v_rndne_f64_e32 v[20:21], v[20:21]
	v_fma_f64 v[18:19], v[18:19], s[18:19], -v[20:21]
	v_cvt_f32_f64_e32 v19, v[18:19]
	v_cos_f32_e32 v18, v19
	v_sin_f32_e32 v20, v19
	v_mul_f32_e32 v19, v35, v22
	v_cvt_f64_f32_e32 v[22:23], v19
	s_lshr_b32 s9, s7, 1
	v_mul_f64 v[24:25], v[22:23], s[18:19]
	s_and_b32 s9, s9, 4
	v_rndne_f64_e32 v[24:25], v[24:25]
	s_or_b32 s10, s8, s9
	s_ashr_i32 s8, s7, 9
	v_fma_f64 v[22:23], v[22:23], s[18:19], -v[24:25]
	s_and_b32 s8, s8, 0x3fffff8
	v_cvt_f32_f64_e32 v21, v[22:23]
	v_or_b32_e32 v22, s8, v30
	s_bfe_u32 s8, s7, 0x60006
	v_lshl_or_b32 v24, v22, 6, s8
	v_mov_b64_e32 v[22:23], s[0:1]
	s_lshr_b32 s11, s10, 2
	v_mad_i64_i32 v[22:23], s[8:9], v24, s33, v[22:23]
	s_mul_i32 s48, s10, 0xc0
	v_lshl_add_u64 v[46:47], v[10:11], 0, s[2:3]
	v_lshl_add_u64 v[26:27], v[22:23], 0, s[48:49]
	v_bitop3_b32 v22, s11, v33, 3 bitop3:0x6c
	s_mov_b32 s8, 0x1b600000
	v_lshlrev_b32_e32 v148, 4, v22
	v_bitop3_b32 v24, s11, v39, 3 bitop3:0x6c
	v_add_co_u32_e32 v54, vcc, s8, v46
	v_lshl_add_u64 v[28:29], v[12:13], 0, s[2:3]
	v_lshl_add_u64 v[22:23], v[26:27], 0, v[148:149]
	v_lshlrev_b32_e32 v148, 4, v24
	v_bitop3_b32 v41, s11, v40, 3 bitop3:0x6c
	v_addc_co_u32_e32 v55, vcc, 0, v47, vcc
	v_lshl_add_u64 v[24:25], v[26:27], 0, v[148:149]
	v_lshlrev_b32_e32 v148, 4, v41
	s_waitcnt vmcnt(15)
	v_mov_b32_e32 v42, v104
	v_mov_b32_e32 v43, v105
	v_mov_b32_e32 v44, v106
	v_mov_b32_e32 v45, v107
	v_mov_b32_e32 v41, v108
	v_mov_b32_e32 v46, v109
	v_cos_f32_e32 v19, v21
	v_sin_f32_e32 v21, v21
	s_mov_b32 s8, 0x12600000
	v_lshl_add_u64 v[24:25], v[24:25], 0, v[0:1]
	v_lshl_add_u64 v[26:27], v[26:27], 0, v[148:149]
	s_add_i32 s7, s7, s84
	s_add_i32 s6, s6, s36
	v_lshl_add_u64 v[26:27], v[26:27], 0, v[0:1]
	v_lshl_add_u64 v[10:11], v[10:11], 0, s[12:13]
	v_lshl_add_u64 v[12:13], v[12:13], 0, s[12:13]
	s_cmpk_gt_i32 s7, 0x7fff
	s_add_i32 s26, s7, s84
	s_cmpk_gt_i32 s26, 0x7fff
	s_cbranch_scc1 .Lrope_nopf_qA
	v_lshl_add_u64 v[122:123], v[12:13], 0, s[12:13]
	v_lshl_add_u64 v[122:123], v[122:123], 0, s[2:3]
	global_load_dwordx4 v[104:107], v[122:123], off
	v_lshl_add_u64 v[124:125], v[10:11], 0, s[12:13]
	v_lshl_add_u64 v[124:125], v[124:125], 0, s[2:3]
	v_lshl_add_u64 v[124:125], v[124:125], 0, s[22:23]
	global_load_dword v108, v[124:125], off offset:128
	global_load_dword v109, v[124:125], off offset:160
.Lrope_nopf_qA:
	v_lshlrev_b32_e32 v64, 16, v42
	v_lshlrev_b32_e32 v58, 16, v46
	v_and_b32_e32 v59, 0xffff0000, v46
	v_lshlrev_b32_e32 v56, 16, v41
	v_and_b32_e32 v57, 0xffff0000, v41
	v_pk_mul_f32 v[76:77], v[56:57], v[56:57]
	v_pk_mul_f32 v[78:79], v[58:59], v[58:59]
	v_and_b32_e32 v65, 0xffff0000, v42
	v_add_f32_e32 v41, v78, v79
	v_add_f32_e32 v76, v76, v77
	v_lshlrev_b32_e32 v60, 16, v43
	v_and_b32_e32 v61, 0xffff0000, v43
	v_pk_mul_f32 v[42:43], v[64:65], v[64:65]
	v_add_f32_e32 v41, v76, v41
	v_add_f32_e32 v41, v41, v42
	v_pk_mul_f32 v[62:63], v[60:61], v[60:61]
	v_add_f32_e32 v41, v41, v43
	v_lshlrev_b32_e32 v70, 16, v44
	v_and_b32_e32 v71, 0xffff0000, v44
	v_add_f32_e32 v41, v41, v62
	v_lshlrev_b32_e32 v66, 16, v45
	v_and_b32_e32 v67, 0xffff0000, v45
	v_pk_mul_f32 v[44:45], v[70:71], v[70:71]
	v_add_f32_e32 v41, v41, v63
	v_add_f32_e32 v41, v41, v44
	v_pk_mul_f32 v[68:69], v[66:67], v[66:67]
	v_add_f32_e32 v41, v41, v45
	v_add_f32_e32 v41, v41, v68
	v_add_f32_e32 v41, v41, v69
	ds_bpermute_b32 v42, v36, v41
	s_waitcnt lgkmcnt(0)
	v_add_f32_e32 v41, v41, v42
	ds_bpermute_b32 v42, v37, v41
	s_waitcnt lgkmcnt(0)
	v_add_f32_e32 v41, v41, v42
	ds_bpermute_b32 v42, v38, v41
	s_waitcnt lgkmcnt(0)
	v_add_f32_e32 v41, v41, v42
	v_fmamk_f32 v41, v41, 0x3c2aaaab, v207
	v_rsq_f32_e32 v41, v41
	s_nop 0
	v_mul_f32_e32 v42, 0x3e16c740, v41
	v_pk_mul_f32 v[44:45], v[42:43], v[70:71] op_sel_hi:[0,1]
	v_pk_mul_f32 v[44:45], v[84:85], v[44:45]
	v_pk_mul_f32 v[50:51], v[42:43], v[66:67] op_sel_hi:[0,1]
	v_pk_mul_f32 v[50:51], v[86:87], v[50:51]
	v_pk_mul_f32 v[52:53], v[42:43], v[64:65] op_sel_hi:[0,1]
	v_pk_mul_f32 v[46:47], v[80:81], v[52:53]
	v_pk_mul_f32 v[52:53], v[42:43], v[60:61] op_sel_hi:[0,1]
	v_pk_mul_f32 v[48:49], v[82:83], v[52:53]
	v_pk_mul_f32 v[52:53], v[88:89], v[42:43] op_sel_hi:[1,0]
	v_pk_mul_f32 v[42:43], v[90:91], v[42:43] op_sel_hi:[1,0]
	v_pk_mul_f32 v[52:53], v[52:53], v[56:57]
	v_pk_mul_f32 v[42:43], v[42:43], v[58:59]
	v_cvt_pk_bf16_f32 v44, v44, v45
	v_pk_mul_f32 v[56:57], v[18:19], v[42:43]
	v_pk_mul_f32 v[42:43], v[20:21], v[42:43]
	v_pk_fma_f32 v[56:57], v[20:21], v[52:53], v[56:57]
	v_pk_fma_f32 v[52:53], v[18:19], v[52:53], v[42:43] neg_lo:[0,0,1] neg_hi:[0,0,1]
	v_cvt_pk_bf16_f32 v42, v46, v47
	v_cvt_pk_bf16_f32 v43, v48, v49
	v_cvt_pk_bf16_f32 v45, v50, v51
	global_store_dwordx4 v[28:29], v[42:45], off
	v_cvt_pk_bf16_f32 v28, v52, v53
	global_store_dword v[54:55], v28, off offset:128
	v_cvt_pk_bf16_f32 v28, v56, v57
	global_store_dword v[54:55], v28, off offset:160
	s_waitcnt vmcnt(12)
	v_mov_b32_e32 v42, v112
	v_mov_b32_e32 v43, v113
	v_mov_b32_e32 v44, v114
	v_mov_b32_e32 v45, v115
	v_mov_b32_e32 v41, v110
	v_mov_b32_e32 v46, v111
	v_lshl_add_u64 v[14:15], v[14:15], 0, s[16:17]
	v_lshl_add_u64 v[16:17], v[16:17], 0, s[16:17]
	s_add_i32 s26, s7, s84
	s_cmpk_gt_i32 s26, 0x7fff
	s_cbranch_scc1 .Lrope_nopf_kA
	v_lshl_add_u64 v[122:123], v[14:15], 0, s[16:17]
	v_lshl_add_u64 v[122:123], v[122:123], 0, s[2:3]
	v_lshl_add_u64 v[122:123], v[122:123], 0, s[24:25]
	global_load_dword v110, v[122:123], off offset:800
	global_load_dword v111, v[122:123], off offset:768
	v_lshl_add_u64 v[124:125], v[16:17], 0, s[16:17]
	v_lshl_add_u64 v[124:125], v[124:125], 0, s[2:3]
	global_load_dwordx4 v[112:115], v[124:125], off
.Lrope_nopf_kA:
	v_lshlrev_b32_e32 v54, 16, v41
	v_lshlrev_b32_e32 v28, 16, v46
	v_and_b32_e32 v29, 0xffff0000, v46
	v_and_b32_e32 v55, 0xffff0000, v41
	v_pk_mul_f32 v[72:73], v[28:29], v[28:29]
	v_pk_mul_f32 v[74:75], v[54:55], v[54:55]
	v_lshlrev_b32_e32 v64, 16, v42
	v_and_b32_e32 v65, 0xffff0000, v42
	v_add_f32_e32 v41, v74, v75
	v_add_f32_e32 v72, v72, v73
	v_lshlrev_b32_e32 v60, 16, v43
	v_and_b32_e32 v61, 0xffff0000, v43
	v_pk_mul_f32 v[42:43], v[64:65], v[64:65]
	v_add_f32_e32 v41, v72, v41
	v_add_f32_e32 v41, v41, v42
	v_pk_mul_f32 v[62:63], v[60:61], v[60:61]
	v_add_f32_e32 v41, v41, v43
	v_lshlrev_b32_e32 v70, 16, v44
	v_and_b32_e32 v71, 0xffff0000, v44
	v_add_f32_e32 v41, v41, v62
	v_lshlrev_b32_e32 v66, 16, v45
	v_and_b32_e32 v67, 0xffff0000, v45
	v_pk_mul_f32 v[44:45], v[70:71], v[70:71]
	v_add_f32_e32 v41, v41, v63
	v_add_f32_e32 v41, v41, v44
	v_pk_mul_f32 v[68:69], v[66:67], v[66:67]
	v_add_f32_e32 v41, v41, v45
	v_add_f32_e32 v41, v41, v68
	v_add_f32_e32 v41, v41, v69
	ds_bpermute_b32 v42, v36, v41
	s_waitcnt lgkmcnt(0)
	v_add_f32_e32 v41, v41, v42
	ds_bpermute_b32 v42, v37, v41
	s_waitcnt lgkmcnt(0)
	v_add_f32_e32 v41, v41, v42
	ds_bpermute_b32 v42, v38, v41
	s_waitcnt lgkmcnt(0)
	v_add_f32_e32 v41, v41, v42
	v_fmamk_f32 v41, v41, 0x3c2aaaab, v207
	v_rsq_f32_e32 v42, v41
	s_nop 0
	v_pk_mul_f32 v[44:45], v[92:93], v[42:43] op_sel_hi:[1,0]
	s_nop 0
	v_pk_mul_f32 v[28:29], v[44:45], v[28:29]
	v_pk_mul_f32 v[44:45], v[94:95], v[42:43] op_sel_hi:[1,0]
	s_nop 0
	v_pk_mul_f32 v[44:45], v[44:45], v[54:55]
	s_nop 0
	v_pk_mul_f32 v[54:55], v[18:19], v[44:45]
	s_nop 0
	v_pk_fma_f32 v[54:55], v[20:21], v[28:29], v[54:55]
	v_pk_mul_f32 v[20:21], v[20:21], v[44:45]
	s_nop 0
	v_pk_fma_f32 v[28:29], v[18:19], v[28:29], v[20:21] neg_lo:[0,0,1] neg_hi:[0,0,1]
	v_pk_mul_f32 v[18:19], v[42:43], v[70:71] op_sel_hi:[0,1]
	v_pk_mul_f32 v[20:21], v[100:101], v[18:19]
	v_pk_mul_f32 v[18:19], v[42:43], v[66:67] op_sel_hi:[0,1]
	v_pk_mul_f32 v[44:45], v[102:103], v[18:19]
	v_pk_mul_f32 v[18:19], v[42:43], v[64:65] op_sel_hi:[0,1]
	v_pk_mul_f32 v[42:43], v[42:43], v[60:61] op_sel_hi:[0,1]
	v_pk_mul_f32 v[18:19], v[96:97], v[18:19]
	v_pk_mul_f32 v[42:43], v[98:99], v[42:43]
	v_cvt_pk_bf16_f32 v18, v18, v19
	v_cvt_pk_bf16_f32 v19, v42, v43
	v_cvt_pk_bf16_f32 v20, v20, v21
	v_cvt_pk_bf16_f32 v21, v44, v45
	global_store_dwordx4 v[22:23], v[18:21], off
	s_nop 1
	v_cvt_pk_bf16_f32 v18, v28, v29
	global_store_dword v[24:25], v18, off
	v_cvt_pk_bf16_f32 v18, v54, v55
	global_store_dword v[26:27], v18, off
	s_cmpk_gt_i32 s7, 0x7fff
	s_cbranch_scc1 .Lrope_exit
	s_and_b32 s8, s7, 0xfff
	s_add_i32 s8, s8, 16
	v_cvt_f32_u32_e32 v22, s8
	s_and_b32 s8, s7, 51
	s_and_b32 s9, s6, 8
	s_or_b32 s8, s9, s8
	v_mul_f32_e32 v18, v34, v22
	v_cvt_f64_f32_e32 v[18:19], v18
	v_mul_f64 v[20:21], v[18:19], s[18:19]
	v_rndne_f64_e32 v[20:21], v[20:21]
	v_fma_f64 v[18:19], v[18:19], s[18:19], -v[20:21]
	v_cvt_f32_f64_e32 v19, v[18:19]
	v_cos_f32_e32 v18, v19
	v_sin_f32_e32 v20, v19
	v_mul_f32_e32 v19, v35, v22
	v_cvt_f64_f32_e32 v[22:23], v19
	s_lshr_b32 s9, s7, 1
	v_mul_f64 v[24:25], v[22:23], s[18:19]
	s_and_b32 s9, s9, 4
	v_rndne_f64_e32 v[24:25], v[24:25]
	s_or_b32 s10, s8, s9
	s_ashr_i32 s8, s7, 9
	v_fma_f64 v[22:23], v[22:23], s[18:19], -v[24:25]
	s_and_b32 s8, s8, 0x3fffff8
	v_cvt_f32_f64_e32 v21, v[22:23]
	v_or_b32_e32 v22, s8, v30
	s_bfe_u32 s8, s7, 0x60006
	v_lshl_or_b32 v24, v22, 6, s8
	v_mov_b64_e32 v[22:23], s[0:1]
	s_lshr_b32 s11, s10, 2
	v_mad_i64_i32 v[22:23], s[8:9], v24, s33, v[22:23]
	s_mul_i32 s48, s10, 0xc0
	v_lshl_add_u64 v[46:47], v[10:11], 0, s[2:3]
	v_lshl_add_u64 v[26:27], v[22:23], 0, s[48:49]
	v_bitop3_b32 v22, s11, v33, 3 bitop3:0x6c
	s_mov_b32 s8, 0x1b600000
	v_lshlrev_b32_e32 v148, 4, v22
	v_bitop3_b32 v24, s11, v39, 3 bitop3:0x6c
	v_add_co_u32_e32 v54, vcc, s8, v46
	v_lshl_add_u64 v[28:29], v[12:13], 0, s[2:3]
	v_lshl_add_u64 v[22:23], v[26:27], 0, v[148:149]
	v_lshlrev_b32_e32 v148, 4, v24
	v_bitop3_b32 v41, s11, v40, 3 bitop3:0x6c
	v_addc_co_u32_e32 v55, vcc, 0, v47, vcc
	v_lshl_add_u64 v[24:25], v[26:27], 0, v[148:149]
	v_lshlrev_b32_e32 v148, 4, v41
	s_waitcnt vmcnt(15)
	v_mov_b32_e32 v42, v116
	v_mov_b32_e32 v43, v117
	v_mov_b32_e32 v44, v118
	v_mov_b32_e32 v45, v119
	v_mov_b32_e32 v41, v120
	v_mov_b32_e32 v46, v121
	v_cos_f32_e32 v19, v21
	v_sin_f32_e32 v21, v21
	s_mov_b32 s8, 0x12600000
	v_lshl_add_u64 v[24:25], v[24:25], 0, v[0:1]
	v_lshl_add_u64 v[26:27], v[26:27], 0, v[148:149]
	s_add_i32 s7, s7, s84
	s_add_i32 s6, s6, s36
	v_lshl_add_u64 v[26:27], v[26:27], 0, v[0:1]
	v_lshl_add_u64 v[10:11], v[10:11], 0, s[12:13]
	v_lshl_add_u64 v[12:13], v[12:13], 0, s[12:13]
	s_cmpk_gt_i32 s7, 0x7fff
	s_add_i32 s26, s7, s84
	s_cmpk_gt_i32 s26, 0x7fff
	s_cbranch_scc1 .Lrope_nopf_qB
	v_lshl_add_u64 v[122:123], v[12:13], 0, s[12:13]
	v_lshl_add_u64 v[122:123], v[122:123], 0, s[2:3]
	global_load_dwordx4 v[116:119], v[122:123], off
	v_lshl_add_u64 v[124:125], v[10:11], 0, s[12:13]
	v_lshl_add_u64 v[124:125], v[124:125], 0, s[2:3]
	v_lshl_add_u64 v[124:125], v[124:125], 0, s[22:23]
	global_load_dword v120, v[124:125], off offset:128
	global_load_dword v121, v[124:125], off offset:160
.Lrope_nopf_qB:
	v_lshlrev_b32_e32 v64, 16, v42
	v_lshlrev_b32_e32 v58, 16, v46
	v_and_b32_e32 v59, 0xffff0000, v46
	v_lshlrev_b32_e32 v56, 16, v41
	v_and_b32_e32 v57, 0xffff0000, v41
	v_pk_mul_f32 v[76:77], v[56:57], v[56:57]
	v_pk_mul_f32 v[78:79], v[58:59], v[58:59]
	v_and_b32_e32 v65, 0xffff0000, v42
	v_add_f32_e32 v41, v78, v79
	v_add_f32_e32 v76, v76, v77
	v_lshlrev_b32_e32 v60, 16, v43
	v_and_b32_e32 v61, 0xffff0000, v43
	v_pk_mul_f32 v[42:43], v[64:65], v[64:65]
	v_add_f32_e32 v41, v76, v41
	v_add_f32_e32 v41, v41, v42
	v_pk_mul_f32 v[62:63], v[60:61], v[60:61]
	v_add_f32_e32 v41, v41, v43
	v_lshlrev_b32_e32 v70, 16, v44
	v_and_b32_e32 v71, 0xffff0000, v44
	v_add_f32_e32 v41, v41, v62
	v_lshlrev_b32_e32 v66, 16, v45
	v_and_b32_e32 v67, 0xffff0000, v45
	v_pk_mul_f32 v[44:45], v[70:71], v[70:71]
	v_add_f32_e32 v41, v41, v63
	v_add_f32_e32 v41, v41, v44
	v_pk_mul_f32 v[68:69], v[66:67], v[66:67]
	v_add_f32_e32 v41, v41, v45
	v_add_f32_e32 v41, v41, v68
	v_add_f32_e32 v41, v41, v69
	ds_bpermute_b32 v42, v36, v41
	s_waitcnt lgkmcnt(0)
	v_add_f32_e32 v41, v41, v42
	ds_bpermute_b32 v42, v37, v41
	s_waitcnt lgkmcnt(0)
	v_add_f32_e32 v41, v41, v42
	ds_bpermute_b32 v42, v38, v41
	s_waitcnt lgkmcnt(0)
	v_add_f32_e32 v41, v41, v42
	v_fmamk_f32 v41, v41, 0x3c2aaaab, v207
	v_rsq_f32_e32 v41, v41
	s_nop 0
	v_mul_f32_e32 v42, 0x3e16c740, v41
	v_pk_mul_f32 v[44:45], v[42:43], v[70:71] op_sel_hi:[0,1]
	v_pk_mul_f32 v[44:45], v[84:85], v[44:45]
	v_pk_mul_f32 v[50:51], v[42:43], v[66:67] op_sel_hi:[0,1]
	v_pk_mul_f32 v[50:51], v[86:87], v[50:51]
	v_pk_mul_f32 v[52:53], v[42:43], v[64:65] op_sel_hi:[0,1]
	v_pk_mul_f32 v[46:47], v[80:81], v[52:53]
	v_pk_mul_f32 v[52:53], v[42:43], v[60:61] op_sel_hi:[0,1]
	v_pk_mul_f32 v[48:49], v[82:83], v[52:53]
	v_pk_mul_f32 v[52:53], v[88:89], v[42:43] op_sel_hi:[1,0]
	v_pk_mul_f32 v[42:43], v[90:91], v[42:43] op_sel_hi:[1,0]
	v_pk_mul_f32 v[52:53], v[52:53], v[56:57]
	v_pk_mul_f32 v[42:43], v[42:43], v[58:59]
	v_cvt_pk_bf16_f32 v44, v44, v45
	v_pk_mul_f32 v[56:57], v[18:19], v[42:43]
	v_pk_mul_f32 v[42:43], v[20:21], v[42:43]
	v_pk_fma_f32 v[56:57], v[20:21], v[52:53], v[56:57]
	v_pk_fma_f32 v[52:53], v[18:19], v[52:53], v[42:43] neg_lo:[0,0,1] neg_hi:[0,0,1]
	v_cvt_pk_bf16_f32 v42, v46, v47
	v_cvt_pk_bf16_f32 v43, v48, v49
	v_cvt_pk_bf16_f32 v45, v50, v51
	global_store_dwordx4 v[28:29], v[42:45], off
	v_cvt_pk_bf16_f32 v28, v52, v53
	global_store_dword v[54:55], v28, off offset:128
	v_cvt_pk_bf16_f32 v28, v56, v57
	global_store_dword v[54:55], v28, off offset:160
	s_waitcnt vmcnt(12)
	v_mov_b32_e32 v42, v128
	v_mov_b32_e32 v43, v129
	v_mov_b32_e32 v44, v130
	v_mov_b32_e32 v45, v131
	v_mov_b32_e32 v41, v126
	v_mov_b32_e32 v46, v127
	v_lshl_add_u64 v[14:15], v[14:15], 0, s[16:17]
	v_lshl_add_u64 v[16:17], v[16:17], 0, s[16:17]
	s_add_i32 s26, s7, s84
	s_cmpk_gt_i32 s26, 0x7fff
	s_cbranch_scc1 .Lrope_nopf_kB
	v_lshl_add_u64 v[122:123], v[14:15], 0, s[16:17]
	v_lshl_add_u64 v[122:123], v[122:123], 0, s[2:3]
	v_lshl_add_u64 v[122:123], v[122:123], 0, s[24:25]
	global_load_dword v126, v[122:123], off offset:800
	global_load_dword v127, v[122:123], off offset:768
	v_lshl_add_u64 v[124:125], v[16:17], 0, s[16:17]
	v_lshl_add_u64 v[124:125], v[124:125], 0, s[2:3]
	global_load_dwordx4 v[128:131], v[124:125], off
.Lrope_nopf_kB:
	v_lshlrev_b32_e32 v54, 16, v41
	v_lshlrev_b32_e32 v28, 16, v46
	v_and_b32_e32 v29, 0xffff0000, v46
	v_and_b32_e32 v55, 0xffff0000, v41
	v_pk_mul_f32 v[72:73], v[28:29], v[28:29]
	v_pk_mul_f32 v[74:75], v[54:55], v[54:55]
	v_lshlrev_b32_e32 v64, 16, v42
	v_and_b32_e32 v65, 0xffff0000, v42
	v_add_f32_e32 v41, v74, v75
	v_add_f32_e32 v72, v72, v73
	v_lshlrev_b32_e32 v60, 16, v43
	v_and_b32_e32 v61, 0xffff0000, v43
	v_pk_mul_f32 v[42:43], v[64:65], v[64:65]
	v_add_f32_e32 v41, v72, v41
	v_add_f32_e32 v41, v41, v42
	v_pk_mul_f32 v[62:63], v[60:61], v[60:61]
	v_add_f32_e32 v41, v41, v43
	v_lshlrev_b32_e32 v70, 16, v44
	v_and_b32_e32 v71, 0xffff0000, v44
	v_add_f32_e32 v41, v41, v62
	v_lshlrev_b32_e32 v66, 16, v45
	v_and_b32_e32 v67, 0xffff0000, v45
	v_pk_mul_f32 v[44:45], v[70:71], v[70:71]
	v_add_f32_e32 v41, v41, v63
	v_add_f32_e32 v41, v41, v44
	v_pk_mul_f32 v[68:69], v[66:67], v[66:67]
	v_add_f32_e32 v41, v41, v45
	v_add_f32_e32 v41, v41, v68
	v_add_f32_e32 v41, v41, v69
	ds_bpermute_b32 v42, v36, v41
	s_waitcnt lgkmcnt(0)
	v_add_f32_e32 v41, v41, v42
	ds_bpermute_b32 v42, v37, v41
	s_waitcnt lgkmcnt(0)
	v_add_f32_e32 v41, v41, v42
	ds_bpermute_b32 v42, v38, v41
	s_waitcnt lgkmcnt(0)
	v_add_f32_e32 v41, v41, v42
	v_fmamk_f32 v41, v41, 0x3c2aaaab, v207
	v_rsq_f32_e32 v42, v41
	s_nop 0
	v_pk_mul_f32 v[44:45], v[92:93], v[42:43] op_sel_hi:[1,0]
	s_nop 0
	v_pk_mul_f32 v[28:29], v[44:45], v[28:29]
	v_pk_mul_f32 v[44:45], v[94:95], v[42:43] op_sel_hi:[1,0]
	s_nop 0
	v_pk_mul_f32 v[44:45], v[44:45], v[54:55]
	s_nop 0
	v_pk_mul_f32 v[54:55], v[18:19], v[44:45]
	s_nop 0
	v_pk_fma_f32 v[54:55], v[20:21], v[28:29], v[54:55]
	v_pk_mul_f32 v[20:21], v[20:21], v[44:45]
	s_nop 0
	v_pk_fma_f32 v[28:29], v[18:19], v[28:29], v[20:21] neg_lo:[0,0,1] neg_hi:[0,0,1]
	v_pk_mul_f32 v[18:19], v[42:43], v[70:71] op_sel_hi:[0,1]
	v_pk_mul_f32 v[20:21], v[100:101], v[18:19]
	v_pk_mul_f32 v[18:19], v[42:43], v[66:67] op_sel_hi:[0,1]
	v_pk_mul_f32 v[44:45], v[102:103], v[18:19]
	v_pk_mul_f32 v[18:19], v[42:43], v[64:65] op_sel_hi:[0,1]
	v_pk_mul_f32 v[42:43], v[42:43], v[60:61] op_sel_hi:[0,1]
	v_pk_mul_f32 v[18:19], v[96:97], v[18:19]
	v_pk_mul_f32 v[42:43], v[98:99], v[42:43]
	v_cvt_pk_bf16_f32 v18, v18, v19
	v_cvt_pk_bf16_f32 v19, v42, v43
	v_cvt_pk_bf16_f32 v20, v20, v21
	v_cvt_pk_bf16_f32 v21, v44, v45
	global_store_dwordx4 v[22:23], v[18:21], off
	s_nop 1
	v_cvt_pk_bf16_f32 v18, v28, v29
	global_store_dword v[24:25], v18, off
	v_cvt_pk_bf16_f32 v18, v54, v55
	global_store_dword v[26:27], v18, off
	s_cmpk_gt_i32 s7, 0x7fff
	s_cbranch_scc0 .LBB0_949
.Lrope_exit:
.LBB0_950:
	s_cmpk_gt_i32 s20, 0x7f
	s_cbranch_scc1 .LBB0_957
	s_mov_b32 s1, s49
	v_readlane_b32 s36, v252, 21
	v_readlane_b32 s49, v252, 34
	v_and_b32_e32 v0, 63, v32
	s_mov_b32 s49, s1
	v_readlane_b32 s0, v253, 61
	v_lshlrev_b32_e32 v148, 2, v0
	v_and_b32_e32 v1, 31, v32
	v_readlane_b32 s50, v252, 35
	v_readlane_b32 s51, v252, 36
	v_readlane_b32 s2, v253, 63
	v_readlane_b32 s3, v254, 0
	v_lshlrev_b32_e32 v2, 2, v1
	v_and_b32_e32 v4, 64, v210
	v_add_u32_e32 v4, 64, v4
	global_load_dword v6, v148, s[50:51]
	s_nop 0
	global_load_dword v7, v148, s[2:3]
	global_load_dword v8, v2, s[50:51] offset:256
	v_xor_b32_e32 v5, 1, v210
	v_cmp_lt_i32_e32 vcc, v5, v4
	s_add_u32 s6, s4, 0x9c400
	s_addc_u32 s7, s5, 0
	v_cndmask_b32_e32 v5, v210, v5, vcc
	v_lshlrev_b32_e32 v9, 2, v5
	v_xor_b32_e32 v5, 2, v210
	v_cmp_lt_i32_e32 vcc, v5, v4
	s_add_u32 s21, s4, 0xac400
	s_addc_u32 s22, s5, 0
	v_cndmask_b32_e32 v5, v210, v5, vcc
	v_lshlrev_b32_e32 v10, 2, v5
	v_xor_b32_e32 v5, 4, v210
	v_cmp_lt_i32_e32 vcc, v5, v4
	s_add_u32 s8, s4, 0xa4400
	v_lshl_add_u64 v[2:3], s[4:5], 0, v[148:149]
	v_cndmask_b32_e32 v5, v210, v5, vcc
	v_lshlrev_b32_e32 v11, 2, v5
	v_xor_b32_e32 v5, 8, v210
	v_cmp_lt_i32_e32 vcc, v5, v4
	s_mov_b64 s[2:3], 0x36a00
	s_addc_u32 s9, s5, 0
	v_cndmask_b32_e32 v5, v210, v5, vcc
	v_lshlrev_b32_e32 v12, 2, v5
	v_xor_b32_e32 v5, 16, v210
	v_cmp_lt_i32_e32 vcc, v5, v4
	v_lshl_add_u64 v[2:3], v[2:3], 0, s[2:3]
	s_mov_b32 s2, 0xc2fc0000
	v_cndmask_b32_e32 v5, v210, v5, vcc
	v_lshlrev_b32_e32 v13, 2, v5
	v_xor_b32_e32 v5, 32, v210
	v_cmp_lt_i32_e32 vcc, v5, v4
	s_add_u32 s10, s4, 0xc4400
	s_addc_u32 s11, s5, 0
	v_cndmask_b32_e32 v4, v210, v5, vcc
	v_lshlrev_b32_e32 v14, 2, v4
	v_and_b32_e32 v4, 15, v32
	v_cvt_f32_ubyte0_e32 v4, v4
	v_mul_f32_e32 v5, 0xbf549a78, v4
	v_cmp_gt_f32_e32 vcc, s2, v5
	v_mov_b32_e32 v5, 0x42800000
	s_add_u32 s23, s4, 0x36400
	v_cndmask_b32_e32 v5, 0, v5, vcc
	v_fmac_f32_e32 v5, 0xbf549a78, v4
	s_addc_u32 s24, s5, 0
	v_exp_f32_e32 v4, v5
	s_add_u32 s12, s4, 0xd4400
	v_and_b32_e32 v5, 16, v32
	s_addc_u32 s13, s5, 0
	v_cmp_eq_u32_e64 s[2:3], 0, v5
	v_not_b32_e32 v5, 63
	s_add_u32 s4, s4, 0xd8400
	v_readlane_b32 s38, v252, 23
	v_readlane_b32 s39, v252, 24
	v_cndmask_b32_e32 v5, 0, v5, vcc
	s_addc_u32 s5, s5, 0
	s_lshl_b32 s15, s14, 5
	v_readlane_b32 s16, v253, 53
	s_mov_b32 s38, 0x6dc9c883
	v_readlane_b32 s1, v253, 62
	v_ldexp_f32 v15, v4, v5
	v_and_b32_e32 v4, 0x80, v148
	s_add_i32 s25, s16, s15
	s_lshl_b32 s14, s14, 6
	v_readlane_b32 s15, v252, 0
	s_mov_b32 s39, 0x3fc45f30
	v_readlane_b32 s36, v254, 30
	v_readlane_b32 s31, v254, 29
	v_cmp_gt_u32_e64 s[0:1], 32, v0
	v_or_b32_e32 v16, 8, v30
	v_or_b32_e32 v17, 0x500, v4
	s_add_i32 s26, s15, s14
	v_readlane_b32 s37, v252, 22
	v_readlane_b32 s40, v252, 25
	v_readlane_b32 s41, v252, 26
	v_readlane_b32 s42, v252, 27
	v_readlane_b32 s43, v252, 28
	v_readlane_b32 s44, v252, 29
	v_readlane_b32 s45, v252, 30
	v_readlane_b32 s46, v252, 31
	v_readlane_b32 s47, v252, 32
	v_readlane_b32 s48, v252, 33
	s_branch .LBB0_953
